# v33 + L0 pass-1 attention loop: next-tile K/V global-load block moved from the post-barrier loop head into the decision region
# baseline (speedup 1.0000x reference)
.LBB0_445:
	s_mul_i32 s14, s8, 0x7400
	v_add_u32_e32 v0, s14, v208
	ds_read_b128 v[126:129], v0
	ds_read_b128 v[130:133], v0 offset:4608
	ds_read_b128 v[134:137], v0 offset:32
	s_waitcnt lgkmcnt(2)
	v_mfma_f32_32x32x16_bf16 v[82:97], v[126:129], v[98:101], v[220:235]
	v_add_f32_e64 v126, v158, 0
	v_add_f32_e64 v127, v159, 0
	v_cvt_pk_bf16_f32 v138, v158, v159
	v_add_f32_e64 v140, v160, v126
	v_add_f32_e64 v141, v161, v127
	v_cvt_pk_bf16_f32 v139, v160, v161
	s_waitcnt lgkmcnt(1)
	v_mfma_f32_32x32x16_bf16 v[66:81], v[130:133], v[98:101], v[220:235]
	ds_read_b128 v[126:129], v0 offset:4640
	v_add_f32_e64 v130, v162, v140
	v_add_f32_e64 v131, v163, v141
	v_cvt_pk_bf16_f32 v140, v162, v163
	v_add_f32_e64 v158, v164, v130
	v_add_f32_e64 v159, v165, v131
	v_cvt_pk_bf16_f32 v141, v164, v165
	s_waitcnt lgkmcnt(1)
	v_mfma_f32_32x32x16_bf16 v[82:97], v[134:137], v[102:105], v[82:97]
	ds_read_b128 v[130:133], v0 offset:64
	v_add_f32_e64 v136, v166, v158
	v_add_f32_e64 v137, v167, v159
	v_cvt_pk_bf16_f32 v134, v166, v167
	v_add_f32_e64 v136, v170, v136
	v_add_f32_e64 v137, v171, v137
	v_cvt_pk_bf16_f32 v135, v170, v171
	s_waitcnt lgkmcnt(1)
	v_mfma_f32_32x32x16_bf16 v[66:81], v[126:129], v[102:105], v[66:81]
	ds_read_b128 v[158:161], v0 offset:4672
	v_add_f32_e64 v126, v174, v136
	v_add_f32_e64 v127, v175, v137
	v_cvt_pk_bf16_f32 v136, v174, v175
	v_add_f32_e64 v162, v178, v126
	v_add_f32_e64 v163, v179, v127
	v_cvt_pk_bf16_f32 v137, v178, v179
	s_waitcnt lgkmcnt(1)
	v_mfma_f32_32x32x16_bf16 v[82:97], v[130:133], v[106:109], v[82:97]
	ds_read_b128 v[126:129], v0 offset:96
	v_add_f32_e64 v132, v168, v162
	v_add_f32_e64 v133, v169, v163
	v_cvt_pk_bf16_f32 v130, v168, v169
	v_add_f32_e64 v132, v172, v132
	v_add_f32_e64 v133, v173, v133
	v_cvt_pk_bf16_f32 v131, v172, v173
	s_waitcnt lgkmcnt(1)
	v_mfma_f32_32x32x16_bf16 v[66:81], v[158:161], v[106:109], v[66:81]
	ds_read_b128 v[162:165], v0 offset:4704
	v_add_f32_e64 v158, v176, v132
	v_add_f32_e64 v159, v177, v133
	v_cvt_pk_bf16_f32 v132, v176, v177
	v_add_f32_e64 v158, v180, v158
	v_add_f32_e64 v159, v181, v159
	v_cvt_pk_bf16_f32 v133, v180, v181
	s_waitcnt lgkmcnt(1)
	v_mfma_f32_32x32x16_bf16 v[82:97], v[126:129], v[110:113], v[82:97]
	v_add_f32_e64 v128, v182, v158
	v_add_f32_e64 v129, v183, v159
	v_cvt_pk_bf16_f32 v126, v182, v183
	v_add_f32_e64 v128, v184, v128
	v_add_f32_e64 v129, v185, v129
	v_cvt_pk_bf16_f32 v127, v184, v185
	s_waitcnt lgkmcnt(0)
	v_mfma_f32_32x32x16_bf16 v[66:81], v[162:165], v[110:113], v[66:81]
	v_add_f32_e64 v158, v186, v128
	v_add_f32_e64 v159, v187, v129
	v_cvt_pk_bf16_f32 v128, v186, v187
	v_add_f32_e64 v158, v188, v158
	v_add_f32_e64 v159, v189, v159
	v_cvt_pk_bf16_f32 v129, v188, v189
	s_andn2_b64 vcc, exec, s[10:11]
	s_cbranch_vccnz .Lattn443_noload
	v_lshl_add_u64 v[236:237], s[94:95], 0, v[156:157]
	v_lshl_add_u64 v[238:239], s[94:95], 0, v[154:155]
	s_nop 0
	global_load_dwordx4 v[114:117], v[238:239], off
	v_add_co_u32_e32 v238, vcc, 0xd008000, v236
	s_nop 1
	v_addc_co_u32_e32 v239, vcc, 0, v237, vcc
	s_nop 0
	global_load_dwordx4 v[118:121], v[238:239], off
	v_add_co_u32_e32 v238, vcc, 0xd00a000, v236
	s_nop 1
	v_addc_co_u32_e32 v239, vcc, 0, v237, vcc
	s_nop 0
	global_load_dwordx4 v[122:125], v[238:239], off
.Lattn443_noload:
	s_nop 0
	v_add_f32_e32 v0, v158, v159
	v_max_f32_e32 v158, v82, v83
	v_max3_f32 v158, v158, v84, v85
	v_max3_f32 v158, v158, v86, v87
	v_max3_f32 v158, v158, v88, v89
	v_max3_f32 v158, v158, v90, v91
	v_max3_f32 v158, v158, v92, v93
	v_max3_f32 v158, v158, v94, v95
	v_max3_f32 v158, v158, v96, v97
	v_max3_f32 v158, v158, v66, v67
	v_max3_f32 v158, v158, v68, v69
	v_max3_f32 v158, v158, v70, v71
	v_max3_f32 v158, v158, v72, v73
	v_max3_f32 v158, v158, v74, v75
	v_max3_f32 v158, v158, v76, v77
	v_max3_f32 v158, v158, v78, v79
	v_max3_f32 v158, v158, v80, v81
	v_add_f32_e32 v206, v206, v0
	ds_bpermute_b32 v0, v190, v158
	s_waitcnt lgkmcnt(0)
	v_max_f32_e32 v0, v158, v0
	v_cmp_lt_f32_e32 vcc, s30, v0
	s_cmp_lg_u64 vcc, 0
	s_cselect_b64 s[12:13], -1, 0
	s_cbranch_vccz .LBB0_447
	v_max_f32_e32 v0, v0, v0
	v_max_f32_e32 v158, 0, v0
	v_exp_f32_e64 v0, -v158
	v_add_f32_e32 v210, v210, v158
	v_xor_b32_e32 v220, 0x80000000, v210
	v_mov_b32_e32 v221, v220
	v_mov_b32_e32 v222, v220
	v_mov_b32_e32 v223, v220
	v_mov_b32_e32 v224, v220
	v_mov_b32_e32 v225, v220
	v_mov_b32_e32 v226, v220
	v_mov_b32_e32 v227, v220
	v_mov_b32_e32 v228, v220
	v_mov_b32_e32 v229, v220
	v_mov_b32_e32 v230, v220
	v_mov_b32_e32 v231, v220
	v_mov_b32_e32 v232, v220
	v_mov_b32_e32 v233, v220
	v_mov_b32_e32 v234, v220
	v_mov_b32_e32 v235, v220
	v_pk_add_f32 v[82:83], v[82:83], v[158:159] op_sel_hi:[1,0] neg_lo:[0,1] neg_hi:[0,1]
	v_pk_add_f32 v[66:67], v[66:67], v[158:159] op_sel_hi:[1,0] neg_lo:[0,1] neg_hi:[0,1]
	v_pk_add_f32 v[84:85], v[84:85], v[158:159] op_sel_hi:[1,0] neg_lo:[0,1] neg_hi:[0,1]
	v_pk_add_f32 v[68:69], v[68:69], v[158:159] op_sel_hi:[1,0] neg_lo:[0,1] neg_hi:[0,1]
	v_pk_add_f32 v[86:87], v[86:87], v[158:159] op_sel_hi:[1,0] neg_lo:[0,1] neg_hi:[0,1]
	v_pk_add_f32 v[70:71], v[70:71], v[158:159] op_sel_hi:[1,0] neg_lo:[0,1] neg_hi:[0,1]
	v_pk_add_f32 v[88:89], v[88:89], v[158:159] op_sel_hi:[1,0] neg_lo:[0,1] neg_hi:[0,1]
	v_pk_add_f32 v[72:73], v[72:73], v[158:159] op_sel_hi:[1,0] neg_lo:[0,1] neg_hi:[0,1]
	v_pk_add_f32 v[90:91], v[90:91], v[158:159] op_sel_hi:[1,0] neg_lo:[0,1] neg_hi:[0,1]
	v_pk_add_f32 v[74:75], v[74:75], v[158:159] op_sel_hi:[1,0] neg_lo:[0,1] neg_hi:[0,1]
	v_pk_add_f32 v[92:93], v[92:93], v[158:159] op_sel_hi:[1,0] neg_lo:[0,1] neg_hi:[0,1]
	v_pk_add_f32 v[76:77], v[76:77], v[158:159] op_sel_hi:[1,0] neg_lo:[0,1] neg_hi:[0,1]
	v_pk_add_f32 v[94:95], v[94:95], v[158:159] op_sel_hi:[1,0] neg_lo:[0,1] neg_hi:[0,1]
	v_pk_add_f32 v[78:79], v[78:79], v[158:159] op_sel_hi:[1,0] neg_lo:[0,1] neg_hi:[0,1]
	v_pk_add_f32 v[96:97], v[96:97], v[158:159] op_sel_hi:[1,0] neg_lo:[0,1] neg_hi:[0,1]
	v_pk_add_f32 v[80:81], v[80:81], v[158:159] op_sel_hi:[1,0] neg_lo:[0,1] neg_hi:[0,1]
	v_mul_f32_e32 v206, v206, v0
	s_branch .LBB0_448
